# v095 + MLA fast path: S0 exps moved into S1 MFMA shadows (3,3,3,4 per gap)
# speedup vs baseline: 1.0097x; 1.0019x over previous
.Lmla_fast_nodma_e:
	s_waitcnt lgkmcnt(0)
	v_mfma_f32_32x32x16_bf16 v[50:65], v[194:197], v[74:77], v[234:249]
	ds_read_b128 v[194:197], v0 offset:6656
	v_add_f32_e32 v254, v202, v203
	v_add_f32_e32 v255, v204, v205
	v_add_f32_e32 v254, v254, v206
	v_add_f32_e32 v255, v255, v207
	v_add_f32_e32 v254, v254, v208
	v_add_f32_e32 v255, v255, v209
	v_mfma_f32_32x32x16_bf16 v[50:65], v[150:153], v[78:81], v[50:65]
	ds_read_b128 v[150:153], v0 offset:6688
	v_add_f32_e32 v254, v254, v210
	v_add_f32_e32 v255, v255, v211
	v_add_f32_e32 v254, v254, v212
	v_add_f32_e32 v255, v255, v213
	v_add_f32_e32 v254, v254, v214
	v_add_f32_e32 v255, v255, v215
	v_mfma_f32_32x32x16_bf16 v[50:65], v[158:161], v[82:85], v[50:65]
	ds_read_b128 v[158:161], v0 offset:6720
	v_add_f32_e32 v254, v254, v216
	v_add_f32_e32 v255, v255, v217
	v_add_f32_e32 v254, v254, v218
	v_add_f32_e32 v255, v255, v219
	v_add_f32_e32 v254, v254, v220
	v_mfma_f32_32x32x16_bf16 v[50:65], v[162:165], v[86:89], v[50:65]
	ds_read_b128 v[162:165], v0 offset:6752
	v_add_f32_e32 v255, v255, v221
	v_add_f32_e32 v254, v254, v222
	v_add_f32_e32 v255, v255, v223
	v_add_f32_e32 v254, v254, v224
	v_add_f32_e32 v255, v255, v225
	v_mfma_f32_32x32x16_bf16 v[50:65], v[174:177], v[90:93], v[50:65]
	ds_read_b128 v[174:177], v0 offset:6784
	v_add_f32_e32 v254, v254, v226
	v_add_f32_e32 v255, v255, v227
	v_add_f32_e32 v254, v254, v228
	v_add_f32_e32 v255, v255, v229
	v_add_f32_e32 v254, v254, v230
	v_mfma_f32_32x32x16_bf16 v[50:65], v[178:181], v[94:97], v[50:65]
	ds_read_b128 v[178:181], v0 offset:6816
	v_add_f32_e32 v255, v255, v231
	v_add_f32_e32 v254, v254, v232
	v_add_f32_e32 v255, v255, v233
	v_add_f32_e32 v254, v254, v255
	v_add_f32_e32 v147, v147, v254
	s_waitcnt lgkmcnt(5)
	v_mfma_f32_32x32x16_bf16 v[34:49], v[194:197], v[74:77], v[234:249]
	ds_read_b64_tr_b16 v[126:127], v142 offset:13312
	ds_read_b64_tr_b16 v[128:129], v142 offset:14848
	ds_read_b64_tr_b16 v[124:125], v142 offset:14912
	ds_read_b64_tr_b16 v[122:123], v142 offset:13376
	s_waitcnt lgkmcnt(8)
	v_mfma_f32_32x32x16_bf16 v[34:49], v[150:153], v[78:81], v[34:49]
	ds_read_b64_tr_b16 v[118:119], v142 offset:16384
	ds_read_b64_tr_b16 v[120:121], v142 offset:17920
	ds_read_b64_tr_b16 v[116:117], v142 offset:17984
	ds_read_b64_tr_b16 v[114:115], v142 offset:16448
	v_exp_f32_e32 v202, v50
	v_exp_f32_e32 v203, v51
	v_exp_f32_e32 v204, v52
	s_waitcnt lgkmcnt(11)
	v_mfma_f32_32x32x16_bf16 v[34:49], v[158:161], v[82:85], v[34:49]
	ds_read_b64_tr_b16 v[110:111], v142 offset:19456
	ds_read_b64_tr_b16 v[112:113], v142 offset:20992
	ds_read_b64_tr_b16 v[108:109], v142 offset:21056
	ds_read_b64_tr_b16 v[106:107], v142 offset:19520
	v_exp_f32_e32 v205, v53
	v_exp_f32_e32 v206, v54
	v_exp_f32_e32 v207, v55
	s_waitcnt lgkmcnt(11)
	v_mfma_f32_32x32x16_bf16 v[34:49], v[162:165], v[86:89], v[34:49]
	ds_read_b64_tr_b16 v[102:103], v142 offset:22528
	ds_read_b64_tr_b16 v[104:105], v142 offset:24064
	ds_read_b64_tr_b16 v[100:101], v142 offset:24128
	ds_read_b64_tr_b16 v[98:99], v142 offset:22592
	v_exp_f32_e32 v208, v56
	v_exp_f32_e32 v209, v57
	v_exp_f32_e32 v210, v58
	v_mfma_f32_32x32x16_bf16 v[34:49], v[174:177], v[90:93], v[34:49]
	v_exp_f32_e32 v211, v59
	v_exp_f32_e32 v212, v60
	v_exp_f32_e32 v213, v61
	v_exp_f32_e32 v214, v62
	v_mfma_f32_32x32x16_bf16 v[34:49], v[178:181], v[94:97], v[34:49]
.Lmla_fast_nostag_e:
	v_exp_f32_e32 v215, v63
	v_exp_f32_e32 v216, v64
	v_exp_f32_e32 v217, v65
	v_cmp_lt_f32_e32 vcc, 0x44800000, v254
	s_cbranch_vccnz .Lmla_fast_rescale_e

.Lmla_fast_nodma_o:
	s_waitcnt lgkmcnt(0)
	v_mfma_f32_32x32x16_bf16 v[50:65], v[194:197], v[74:77], v[234:249]
	ds_read_b128 v[194:197], v0 offset:6656
	v_add_f32_e32 v254, v202, v203
	v_add_f32_e32 v255, v204, v205
	v_add_f32_e32 v254, v254, v206
	v_add_f32_e32 v255, v255, v207
	v_add_f32_e32 v254, v254, v208
	v_add_f32_e32 v255, v255, v209
	v_mfma_f32_32x32x16_bf16 v[50:65], v[150:153], v[78:81], v[50:65]
	ds_read_b128 v[150:153], v0 offset:6688
	v_add_f32_e32 v254, v254, v210
	v_add_f32_e32 v255, v255, v211
	v_add_f32_e32 v254, v254, v212
	v_add_f32_e32 v255, v255, v213
	v_add_f32_e32 v254, v254, v214
	v_add_f32_e32 v255, v255, v215
	v_mfma_f32_32x32x16_bf16 v[50:65], v[158:161], v[82:85], v[50:65]
	ds_read_b128 v[158:161], v0 offset:6720
	v_add_f32_e32 v254, v254, v216
	v_add_f32_e32 v255, v255, v217
	v_add_f32_e32 v254, v254, v218
	v_add_f32_e32 v255, v255, v219
	v_add_f32_e32 v254, v254, v220
	v_mfma_f32_32x32x16_bf16 v[50:65], v[162:165], v[86:89], v[50:65]
	ds_read_b128 v[162:165], v0 offset:6752
	v_add_f32_e32 v255, v255, v221
	v_add_f32_e32 v254, v254, v222
	v_add_f32_e32 v255, v255, v223
	v_add_f32_e32 v254, v254, v224
	v_add_f32_e32 v255, v255, v225
	v_mfma_f32_32x32x16_bf16 v[50:65], v[174:177], v[90:93], v[50:65]
	ds_read_b128 v[174:177], v0 offset:6784
	v_add_f32_e32 v254, v254, v226
	v_add_f32_e32 v255, v255, v227
	v_add_f32_e32 v254, v254, v228
	v_add_f32_e32 v255, v255, v229
	v_add_f32_e32 v254, v254, v230
	v_mfma_f32_32x32x16_bf16 v[50:65], v[178:181], v[94:97], v[50:65]
	ds_read_b128 v[178:181], v0 offset:6816
	v_add_f32_e32 v255, v255, v231
	v_add_f32_e32 v254, v254, v232
	v_add_f32_e32 v255, v255, v233
	v_add_f32_e32 v254, v254, v255
	v_add_f32_e32 v147, v147, v254
	s_waitcnt lgkmcnt(5)
	v_mfma_f32_32x32x16_bf16 v[34:49], v[194:197], v[74:77], v[234:249]
	ds_read_b64_tr_b16 v[126:127], v142 offset:13312
	ds_read_b64_tr_b16 v[128:129], v142 offset:14848
	ds_read_b64_tr_b16 v[124:125], v142 offset:14912
	ds_read_b64_tr_b16 v[122:123], v142 offset:13376
	s_waitcnt lgkmcnt(8)
	v_mfma_f32_32x32x16_bf16 v[34:49], v[150:153], v[78:81], v[34:49]
	ds_read_b64_tr_b16 v[118:119], v142 offset:16384
	ds_read_b64_tr_b16 v[120:121], v142 offset:17920
	ds_read_b64_tr_b16 v[116:117], v142 offset:17984
	ds_read_b64_tr_b16 v[114:115], v142 offset:16448
	v_exp_f32_e32 v202, v50
	v_exp_f32_e32 v203, v51
	v_exp_f32_e32 v204, v52
	s_waitcnt lgkmcnt(11)
	v_mfma_f32_32x32x16_bf16 v[34:49], v[158:161], v[82:85], v[34:49]
	ds_read_b64_tr_b16 v[110:111], v142 offset:19456
	ds_read_b64_tr_b16 v[112:113], v142 offset:20992
	ds_read_b64_tr_b16 v[108:109], v142 offset:21056
	ds_read_b64_tr_b16 v[106:107], v142 offset:19520
	v_exp_f32_e32 v205, v53
	v_exp_f32_e32 v206, v54
	v_exp_f32_e32 v207, v55
	s_waitcnt lgkmcnt(11)
	v_mfma_f32_32x32x16_bf16 v[34:49], v[162:165], v[86:89], v[34:49]
	ds_read_b64_tr_b16 v[102:103], v142 offset:22528
	ds_read_b64_tr_b16 v[104:105], v142 offset:24064
	ds_read_b64_tr_b16 v[100:101], v142 offset:24128
	ds_read_b64_tr_b16 v[98:99], v142 offset:22592
	v_exp_f32_e32 v208, v56
	v_exp_f32_e32 v209, v57
	v_exp_f32_e32 v210, v58
	v_mfma_f32_32x32x16_bf16 v[34:49], v[174:177], v[90:93], v[34:49]
	v_exp_f32_e32 v211, v59
	v_exp_f32_e32 v212, v60
	v_exp_f32_e32 v213, v61
	v_exp_f32_e32 v214, v62
	v_mfma_f32_32x32x16_bf16 v[34:49], v[178:181], v[94:97], v[34:49]
	s_waitcnt vmcnt(0) lgkmcnt(0)
	s_barrier
